# cvhost group version: 4 waves convert one 64x32 item per iteration through a per-group 4.5 KiB LDS tile; full-line reads and full-line stores
# speedup vs baseline: 1.0152x; 1.0152x over previous
; template <int ABL> __device__ __forceinline__ void attn_unit(int b, int h, int qb, const bf16_t* Q, const bf16_t* KV, const bf16_t* KPE, bf16_t* MG, float* ssqa, LAS unsigned char* L) {
;   const int tid = threadIdx.x, lane = fresh_lane(), r32 = lane & 31, hi = lane >> 5; const int wid = __builtin_amdgcn_readfirstlane(tid >> 6);
;   LAS unsigned char* Vl = L + OFF_V; LAS unsigned char* Kl = L + OFF_K;
;   LAS float* wsf = (LAS float*)(L + OFF_WS) + wid * 64; LAS float* li_l = wsf; LAS float* al_l = wsf + 32;
;   LAS unsigned char* Qr = (wid < 5) ? L + OFF_QR + wid * 8192 : L + OFF_QR_HI + (wid - 5) * 8192;
;   float m_reg = -1e30f, l_reg = 0; f32x16 o[4] = {}; bf16x8 qr[4];
;   const size_t rowbase = (size_t)b * SEQ; const int q0 = qb * 256;
;   const int kro = r32 * 128, ksw = (r32 >> 1) & 7;
;   const int krow = wid * 8 + (lane >> 3), kcl = (lane & 7) ^ ((krow >> 1) & 7);
;   const unsigned voffK = (unsigned)(krow * LDKV + kcl * 8) * 2u, voffP = (unsigned)(krow * LDKPE + kcl * 8) * 2u;
;   const int vj = (lane >> 2) & 7, vkg = wid >> 1, vk = (vkg >> 1) * 16 + (vj >> 2) * 8 + (vkg & 1) * 4 + (vj & 3), vc = 32 * (2 * (wid & 1) + (lane >> 5)) + (lane & 3) * 8;
;   const unsigned voffV = (unsigned)(vk * LDKV + vc) * 2u;
;   const char* Kt = (const char*)(KV + rowbase * LDKV + h * 256); const char* Pt = (const char*)(KPE + rowbase * LDKPE);
;   constexpr size_t KSTEP = (size_t)KVBLK * LDKV * 2, PSTEP = (size_t)KVBLK * LDKPE * 2;
;     ...
;   DMA_K(0, 0); DMA_V(0, 0); DMA_K(1, 1);
;   const bf16_t* Qw = Q + (rowbase + q0 + wid * QBLK + r32) * LDQ + h * 192 + hi * 8;
; #pragma unroll
;   for (int d0 = 0; d0 < 4; ++d0) qr[d0] = ld8(Qw + d0 * 16);
; #pragma unroll
;   for (int dd = 0; dd < 8; ++dd) *reinterpret_cast<LAS bf16x8*>(Qr + (dd >> 2) * 4096 + kro + (((2 * (dd & 3) + hi) ^ ksw) << 4)) = ld8(Qw + (4 + dd) * 16);
; __device__ __forceinline__ int p0_super(int s, int q) {
;     int base, nbw;
;     if (s < F_O / 4) { base = 0; nbw = 64; }
;     else if ((s -= F_O / 4) < F_UP / 4) { base = F_O; nbw = 352; }
;     else if ((s -= F_UP / 4) < F_DN / 4) { base = F_O + F_UP; nbw = 64; }
;     else if ((s -= F_DN / 4) < F_IN / 4) { base = F_O + F_UP + F_DN; nbw = 128; }
;     else if ((s -= F_IN / 4) < F_Q / 4) { base = F_O + F_UP + F_DN + F_IN; nbw = 32; }
;     else { s -= F_Q / 4; base = F_O + F_UP + F_DN + F_IN + F_Q; nbw = 64; }
.LBB0_746:
	v_readlane_b32 s100, v247, 0
	v_readlane_b32 s101, v247, 1
	s_mov_b32 s87, 0
	s_lshr_b32 s32, s2, 8
	s_mul_i32 s32, s32, 19
	s_sub_u32 s100, s100, 0xa0
	s_subb_u32 s101, s101, 0
	v_readfirstlane_b32 s82, v0
	s_ashr_i32 s54, s2, 7
	s_lshr_b32 s58, s82, 4
	s_lshr_b32 s83, s82, 6
	s_ashr_i32 s55, s54, 31
	s_lshl_b32 s6, s2, 8
	s_and_b32 s84, s58, 0xffff0
	s_lshr_b32 s58, s82, 5
	s_bfe_u32 s56, s2, 0x30004
	v_mbcnt_lo_u32_b32 v56, -1, 0
	v_mbcnt_hi_u32_b32 v56, -1, v56
	s_lshl_b32 s57, s83, 13
	v_ashrrev_i32_e32 v164, 5, v56
	s_lshl_b64 s[0:1], s[54:55], 12
	s_and_b32 s6, s6, 0xf00
	s_and_b32 s85, s58, 4
	s_and_b32 s58, s58, 2
	s_lshl_b64 s[72:73], s[54:55], 24
	v_ashrrev_i32_e32 v57, 3, v56
	v_add_u32_e32 v6, s58, v164
	s_add_u32 s58, s36, s72
	v_lshl_add_u32 v4, s83, 3, v57
	s_addc_u32 s59, s37, s73
	s_lshl_b32 s60, s56, 9
	v_lshrrev_b32_e32 v2, 1, v4
	s_add_u32 s70, s58, s60
	v_xor_b32_e32 v2, v2, v56
	s_addc_u32 s71, s59, 0
	s_lshl_b64 s[74:75], s[54:55], 19
	v_lshlrev_b32_e32 v2, 4, v2
	s_add_u32 s54, s22, s74
	v_and_b32_e32 v58, 0x70, v2
	s_addc_u32 s55, s23, s75
	s_lshl_b32 s86, s83, 10
	v_lshrrev_b32_e32 v1, 1, v56
	v_lshl_or_b32 v2, v4, 12, v58
	s_add_i32 s58, s86, 0
	v_and_b32_e32 v59, 8, v1
	v_bfe_u32 v60, v56, 2, 2
	v_lshlrev_b32_e32 v62, 4, v56
	s_add_i32 s59, s58, 0x8000
	v_lshl_add_u64 v[52:53], s[70:71], 0, v[2:3]
	s_mov_b64 s[60:61], 0x80
	v_or3_b32 v5, v59, v60, s84
	v_and_b32_e32 v61, 48, v62
	s_mov_b32 m0, s59
	v_lshl_add_u64 v[8:9], v[52:53], 0, s[60:61]
	s_add_i32 s60, s58, 0xa000
	v_or_b32_e32 v5, s85, v5
	v_lshl_or_b32 v6, v6, 6, v61
	global_load_lds_dwordx4 v2, s[70:71]
	s_mov_b32 m0, s60
	s_add_i32 s61, s58, 0xc000
	v_lshl_or_b32 v4, v4, 7, v58
	v_lshl_add_u32 v6, v5, 12, v6
	global_load_lds_dwordx4 v[8:9], off
	v_mov_b32_e32 v5, v3
	s_mov_b32 m0, s61
	v_mov_b32_e32 v7, v3
	v_lshl_add_u64 v[54:55], s[54:55], 0, v[4:5]
	global_load_lds_dwordx4 v4, s[54:55]
	v_lshl_add_u64 v[142:143], s[70:71], 0, v[6:7]
	s_mov_b64 s[54:55], 0x100
	v_lshl_add_u64 v[4:5], v[142:143], 0, s[54:55]
	s_mov_b32 m0, s58
	s_mov_b64 s[54:55], 0x20100
	s_add_i32 s77, s58, 0x2000
	global_load_lds_dwordx4 v[4:5], off
	v_lshl_add_u64 v[4:5], v[142:143], 0, s[54:55]
	s_mov_b32 m0, s77
	s_add_i32 s78, s58, 0xe000
	s_mov_b64 s[54:55], 0x40000
	global_load_lds_dwordx4 v[4:5], off
	v_lshl_add_u64 v[4:5], v[52:53], 0, s[54:55]
	s_mov_b32 m0, s78
	s_mov_b64 s[54:55], 0x40080
	global_load_lds_dwordx4 v[4:5], off
	v_lshl_add_u64 v[4:5], v[52:53], 0, s[54:55]
	s_add_i32 m0, s58, 0x10000
	s_or_b32 s0, s0, s6
	global_load_lds_dwordx4 v[4:5], off
	s_add_i32 m0, s58, 0x12000
	s_lshl_b32 s6, s83, 5
	v_and_b32_e32 v163, 31, v56
	s_mov_b64 s[54:55], 0x2000
	s_add_u32 s70, s0, s6
	v_lshl_add_u64 v[4:5], v[54:55], 0, s[54:55]
	v_or_b32_e32 v2, s70, v163
	s_movk_i32 s0, 0xc00
	global_load_lds_dwordx4 v[4:5], off
	s_addc_u32 s71, s1, 0
	v_mad_u64_u32 v[4:5], s[0:1], v2, s0, v[138:139]
	v_mad_i32_i24 v5, s71, v141, v5
	s_mul_i32 s6, s56, 0x180
	v_lshlrev_b32_e32 v6, 3, v164
	v_lshl_add_u64 v[4:5], v[4:5], 0, s[6:7]
	v_ashrrev_i32_e32 v7, 31, v6
	v_lshl_add_u64 v[8:9], v[6:7], 1, v[4:5]
	global_load_dwordx4 v[126:129], v[8:9], off
	global_load_dwordx4 v[122:125], v[8:9], off offset:32
	global_load_dwordx4 v[118:121], v[8:9], off offset:64
	global_load_dwordx4 v[114:117], v[8:9], off offset:96
	global_load_dwordx4 v[4:7], v[8:9], off offset:128
	s_add_i32 s6, s57, 0
	s_cmpk_lt_u32 s82, 0x140
	s_mov_b32 s0, 0x14800
	s_cselect_b32 s0, s0, 0x16400
	s_add_i32 s0, s6, s0
	v_lshlrev_b32_e32 v63, 7, v163
	v_bitop3_b32 v10, v1, v164, 7 bitop3:0x6c
	v_add_u32_e32 v2, s0, v63
	v_lshlrev_b32_e32 v172, 4, v10
	v_add_u32_e32 v171, v2, v172
	v_add_u32_e32 v10, 2, v164
	v_bitop3_b32 v10, v10, v1, 7 bitop3:0x78
	v_lshlrev_b32_e32 v173, 4, v10
	v_add_u32_e32 v170, v2, v173
	v_add_u32_e32 v10, 4, v164
	v_bitop3_b32 v10, v10, v1, 7 bitop3:0x78
	v_lshlrev_b32_e32 v174, 4, v10
	v_add_u32_e32 v169, v2, v174
	v_add_u32_e32 v10, 6, v164
	v_bitop3_b32 v1, v10, v1, 7 bitop3:0x78
	v_lshlrev_b32_e32 v175, 4, v1
	v_add_u32_e32 v168, v2, v175
	v_add_u32_e32 v1, 0, v63
	v_add_u32_e32 v178, v1, v172
	s_waitcnt vmcnt(0)
	ds_write_b128 v171, v[4:7]
	global_load_dwordx4 v[4:7], v[8:9], off offset:160
	s_waitcnt vmcnt(0)
	ds_write_b128 v170, v[4:7]
	global_load_dwordx4 v[4:7], v[8:9], off offset:192
	s_waitcnt vmcnt(0)
	ds_write_b128 v169, v[4:7]
	global_load_dwordx4 v[4:7], v[8:9], off offset:224
	s_waitcnt vmcnt(0)
	ds_write_b128 v168, v[4:7]
	global_load_dwordx4 v[4:7], v[8:9], off offset:256
	s_waitcnt vmcnt(0)
	ds_write_b128 v171, v[4:7] offset:4096
	global_load_dwordx4 v[4:7], v[8:9], off offset:288
	s_waitcnt vmcnt(0)
	ds_write_b128 v170, v[4:7] offset:4096
	global_load_dwordx4 v[4:7], v[8:9], off offset:320
	s_waitcnt vmcnt(0)
	ds_write_b128 v169, v[4:7] offset:4096
	global_load_dwordx4 v[4:7], v[8:9], off offset:352
	s_waitcnt vmcnt(0)
	ds_write_b128 v168, v[4:7] offset:4096
	s_waitcnt vmcnt(0)
	s_waitcnt lgkmcnt(0)
	s_barrier
	ds_read_b128 v[4:7], v178 offset:32768
	ds_read_b128 v[8:11], v178 offset:36864
	s_waitcnt lgkmcnt(1)
	v_mfma_f32_32x32x16_bf16 v[36:51], v[4:7], v[126:129], 0
	v_add_u32_e32 v179, v1, v173
	ds_read_b128 v[12:15], v179 offset:32768
	ds_read_b128 v[16:19], v179 offset:36864
	s_waitcnt lgkmcnt(2)
	v_mfma_f32_32x32x16_bf16 v[20:35], v[8:11], v[126:129], 0
	s_waitcnt lgkmcnt(1)
	v_mfma_f32_32x32x16_bf16 v[36:51], v[12:15], v[122:125], v[36:51]
	v_add_u32_e32 v177, v1, v174
	ds_read_b128 v[4:7], v177 offset:32768
	ds_read_b128 v[8:11], v177 offset:36864
	s_waitcnt lgkmcnt(2)
	v_mfma_f32_32x32x16_bf16 v[20:35], v[16:19], v[122:125], v[20:35]
	s_waitcnt lgkmcnt(1)
	v_mfma_f32_32x32x16_bf16 v[36:51], v[4:7], v[118:121], v[36:51]
	v_add_u32_e32 v176, v1, v175
	ds_read_b128 v[12:15], v176 offset:32768
	ds_read_b128 v[16:19], v176 offset:36864
	s_waitcnt lgkmcnt(2)
	v_mfma_f32_32x32x16_bf16 v[20:35], v[8:11], v[118:121], v[20:35]
	s_waitcnt lgkmcnt(1)
	v_mfma_f32_32x32x16_bf16 v[36:51], v[12:15], v[114:117], v[36:51]
	ds_read_b128 v[4:7], v178 offset:40960
	ds_read_b128 v[8:11], v178 offset:45056
	ds_read_b128 v[64:67], v171
	s_waitcnt lgkmcnt(3)
	v_mfma_f32_32x32x16_bf16 v[20:35], v[16:19], v[114:117], v[20:35]
	s_waitcnt lgkmcnt(0)
	v_mfma_f32_32x32x16_bf16 v[36:51], v[4:7], v[64:67], v[36:51]
	ds_read_b128 v[12:15], v179 offset:40960
	ds_read_b128 v[16:19], v179 offset:45056
	ds_read_b128 v[68:71], v170
	v_mfma_f32_32x32x16_bf16 v[20:35], v[8:11], v[64:67], v[20:35]
	s_waitcnt lgkmcnt(0)
	v_mfma_f32_32x32x16_bf16 v[36:51], v[12:15], v[68:71], v[36:51]
	ds_read_b128 v[4:7], v177 offset:40960
	ds_read_b128 v[8:11], v177 offset:45056
	ds_read_b128 v[64:67], v169
	v_mfma_f32_32x32x16_bf16 v[20:35], v[16:19], v[68:71], v[20:35]
	s_waitcnt lgkmcnt(0)
	v_mfma_f32_32x32x16_bf16 v[36:51], v[4:7], v[64:67], v[36:51]
	ds_read_b128 v[12:15], v176 offset:40960
	ds_read_b128 v[16:19], v176 offset:45056
	ds_read_b128 v[68:71], v168
	v_mfma_f32_32x32x16_bf16 v[20:35], v[8:11], v[64:67], v[20:35]
	s_waitcnt lgkmcnt(0)
	v_mfma_f32_32x32x16_bf16 v[36:51], v[12:15], v[68:71], v[36:51]
	ds_read_b128 v[4:7], v178 offset:49152
	ds_read_b128 v[8:11], v178 offset:53248
	ds_read_b128 v[64:67], v171 offset:4096
	v_mfma_f32_32x32x16_bf16 v[20:35], v[16:19], v[68:71], v[20:35]
	s_waitcnt lgkmcnt(0)
	v_mfma_f32_32x32x16_bf16 v[36:51], v[4:7], v[64:67], v[36:51]
	ds_read_b128 v[12:15], v179 offset:49152
	ds_read_b128 v[16:19], v179 offset:53248
	ds_read_b128 v[68:71], v170 offset:4096
	v_mfma_f32_32x32x16_bf16 v[20:35], v[8:11], v[64:67], v[20:35]
	s_waitcnt lgkmcnt(0)
	v_mfma_f32_32x32x16_bf16 v[36:51], v[12:15], v[68:71], v[36:51]
	ds_read_b128 v[4:7], v177 offset:49152
	ds_read_b128 v[8:11], v177 offset:53248
	ds_read_b128 v[64:67], v169 offset:4096
	v_mfma_f32_32x32x16_bf16 v[20:35], v[16:19], v[68:71], v[20:35]
	s_waitcnt lgkmcnt(0)
	v_mfma_f32_32x32x16_bf16 v[36:51], v[4:7], v[64:67], v[36:51]
	ds_read_b128 v[12:15], v176 offset:49152
	ds_read_b128 v[16:19], v176 offset:53248
	ds_read_b128 v[68:71], v168 offset:4096
	v_mfma_f32_32x32x16_bf16 v[20:35], v[8:11], v[64:67], v[20:35]
	s_waitcnt lgkmcnt(0)
	v_mfma_f32_32x32x16_bf16 v[36:51], v[12:15], v[68:71], v[36:51]
	v_mfma_f32_32x32x16_bf16 v[20:35], v[16:19], v[68:71], v[20:35]
	s_nop 10
	v_max_f32_e32 v1, v37, v37
	v_max_f32_e32 v2, v36, v36
	v_max_f32_e32 v1, v2, v1
	v_max3_f32 v2, v38, v39, v21
	v_max3_f32 v1, v1, v20, v22
	v_max3_f32 v1, v1, v23, v40
	v_max3_f32 v2, v2, v42, v43
	v_max3_f32 v1, v1, v41, v24
	v_max3_f32 v2, v2, v26, v27
	v_max3_f32 v1, v1, v25, v44
	v_max3_f32 v2, v2, v46, v47
	v_max3_f32 v1, v1, v45, v28
	v_max3_f32 v2, v2, v30, v31
	v_max3_f32 v1, v1, v29, v48
	v_max3_f32 v2, v2, v50, v51
	v_max3_f32 v1, v1, v49, v32
	v_max3_f32 v2, v2, v34, v35
	v_max3_f32 v1, v1, v33, v2
	v_mov_b32_e32 v2, v1
	s_nop 1
	v_permlane32_swap_b32_e32 v1, v2
	v_max_f32_e32 v2, v2, v2
	v_max_f32_e32 v1, v1, v1
	v_max_f32_e32 v1, v1, v2
	v_add_f32_e32 v2, 0x7149f2ca, v1
	v_cmp_ge_f32_e32 vcc, s3, v2
	s_cmp_eq_u64 vcc, exec
	s_cbranch_scc0 .LBB0_794
	v_mov_b32_e32 v140, 0xf149f2ca
	v_mov_b32_e32 v180, 1.0

; __device__ __forceinline__ P0Desc p0_desc(int r, int lane, const P0Ptrs& a) {
;     const int kk = lane >> 3, n4 = (lane & 7) * 4; P0Desc d; d.gs = 1.f;
;     int kb, n, sc, nsrc, ldt; const float* W; bf16_t* WT; const float* ks;
;     if (r < F_O) { kb = r >> 6; n = 32 * (r & 63) + n4; sc = n; W = a.w_o; nsrc = 2048; WT = a.WoT; ldt = 2048; ks = (kb < 16) ? a.on_a : (a.on_c - 1024); }
;     else if ((r -= F_O) < F_UP) { kb = r / 352; n = 32 * (r % 352) + n4; sc = ((n >> 7) & 1) * DFF + (n >> 8) * 128 + (n & 127); W = a.w_up; nsrc = 2 * DFF; WT = a.WupT; ldt = 2048; ks = a.ffn_g; }
;     else if ((r -= F_UP) < F_DN) { kb = r >> 6; n = 32 * (r & 63) + n4; sc = n; W = a.w_dn; nsrc = 2048; WT = a.WdT; ldt = DFF; ks = nullptr; }
;     else if ((r -= F_DN) < F_IN) { kb = r >> 7; n = 32 * (r & 127) + n4;
;         if (n < 1024) sc = n; else if (n < 2048) sc = n + 64; else sc = (((n >> 7) & 1) ? 3136 : 2112) + 128 * ((n - 2048) >> 8) + (n & 127);
;         W = a.w_in; nsrc = INW; WT = a.WinT; ldt = 2048; ks = a.attn_g; }
;     else if ((r -= F_IN) < F_Q) { kb = r >> 5; n = 32 * (6 * ((r & 31) >> 2) + (r & 3)) + n4; sc = n; W = a.w_qb; nsrc = 1536; WT = a.WqT; ldt = 2048; ks = a.qa_g; d.gs = QSCALE; }
;     else { r -= F_Q; kb = r >> 6; n = 32 * (r & 63) + n4; sc = n; W = a.w_kvb; nsrc = 2048; WT = a.WkvT; ldt = 2048; ks = a.kva_g; }
;     const int k0 = 64 * kb + 8 * kk;
;     d.src = W + (size_t)k0 * nsrc + sc; d.nsrc = nsrc; d.dst = WT + (size_t)n * ldt + k0; d.ldt = ldt; d.ks = ks ? ks + k0 : nullptr;
;     return d;
; }
; __device__ __forceinline__ int p0_super(int s, int q) {
;     int base, nbw;
;     if (s < F_O / 4) { base = 0; nbw = 64; }
;     else if ((s -= F_O / 4) < F_UP / 4) { base = F_O; nbw = 352; }
;     else if ((s -= F_UP / 4) < F_DN / 4) { base = F_O + F_UP; nbw = 64; }
;     else if ((s -= F_DN / 4) < F_IN / 4) { base = F_O + F_UP + F_DN; nbw = 128; }
;     else if ((s -= F_IN / 4) < F_Q / 4) { base = F_O + F_UP + F_DN + F_IN; nbw = 32; }
;     else { s -= F_Q / 4; base = F_O + F_UP + F_DN + F_IN + F_Q; nbw = 64; }
;     return base + ((s / nbw) * 4 + q) * nbw + (s % nbw);
; }
; template <int NB>
; __device__ __forceinline__ void p0_batch(int it0, int stride, int lane, const P0Ptrs& a) {
;     f32x4 v[NB][8], s0[NB], s1[NB]; P0Desc d[NB];
; #pragma unroll
.LBB0_759:
	v_lshl_add_u64 v[112:113], s[28:29], 0, v[146:147]
	s_mov_b64 s[54:55], 0x18fc0000
	s_mov_b32 m0, s78
	v_lshl_add_u64 v[100:101], v[112:113], 0, s[54:55]
	s_waitcnt vmcnt(0)
	s_barrier
	global_load_lds_dwordx4 v[100:101], off
	v_lshl_add_u64 v[100:101], v[112:113], 0, s[38:39]
	s_add_i32 m0, s78, 0x2000
	v_lshl_add_u64 v[136:137], s[28:29], 0, v[144:145]
	global_load_lds_dwordx4 v[100:101], off
	v_lshl_add_u64 v[100:101], v[136:137], 0, s[40:41]
	s_add_i32 m0, s78, 0x4000
	v_lshl_add_u64 v[134:135], s[28:29], 0, v[148:149]
	global_load_lds_dwordx4 v[100:101], off
	v_lshl_add_u64 v[100:101], v[134:135], 0, s[42:43]
	s_mov_b32 m0, s58
	global_load_lds_dwordx4 v[100:101], off
	v_lshl_add_u64 v[100:101], v[134:135], 0, s[44:45]
	s_mov_b32 m0, s77
	global_load_lds_dwordx4 v[100:101], off
	s_lshr_b32 s86, s2, 8
	s_mul_i32 s86, s86, 18
	s_add_i32 s86, s86, 19
	s_cmp_eq_u32 s87, 0
	s_cbranch_scc1 .Lg_nocons
	s_cmp_gt_u32 s32, s86
	s_cbranch_scc1 .Lg_nocons
	s_mov_b64 s[92:93], s[82:83]
	s_mov_b32 s91, s84
	s_cmp_lg_u32 s85, 0
	s_cbranch_scc1 .Lg_nomul
	v_mul_f32_e32 v238, v250, v238
	v_mul_f32_e32 v239, v250, v239
	v_mul_f32_e32 v240, v250, v240
	v_mul_f32_e32 v241, v250, v241
	v_mul_f32_e32 v242, v251, v242
	v_mul_f32_e32 v243, v251, v243
	v_mul_f32_e32 v244, v251, v244
	v_mul_f32_e32 v245, v251, v245
.Lg_nomul:
	v_readfirstlane_b32 s98, v0
	v_and_b32_e32 v76, 63, v0
	v_lshrrev_b32_e32 v77, 3, v76
	v_and_b32_e32 v78, 7, v76
	v_cvt_pk_bf16_f32 v100, v238, v242
	v_cvt_pk_bf16_f32 v101, v239, v243
	v_cvt_pk_bf16_f32 v102, v240, v244
	v_cvt_pk_bf16_f32 v103, v241, v245
	s_lshr_b32 s98, s98, 6
	s_and_b32 s99, s98, 3
	s_lshl_b32 s99, s99, 5
	s_cmp_lt_u32 s98, 4
	s_mov_b32 s98, 0x26400
	s_cselect_b32 s98, 0x1e800, s98
	s_add_i32 s98, s98, s99
	v_mul_u32_u24_e32 v81, 0x240, v78
	v_lshl_add_u32 v81, v77, 2, v81
	v_add_u32_e32 v81, s98, v81
	ds_write_b32 v81, v100
	ds_write_b32 v81, v101 offset:144
	ds_write_b32 v81, v102 offset:288
	ds_write_b32 v81, v103 offset:432
	s_waitcnt lgkmcnt(0)
.Lg_nocons:
	s_cmp_ge_u32 s32, s86
	s_cbranch_scc1 .Lg_inc
	s_cmp_eq_u32 s87, 0
	s_cbranch_scc1 .Lg_ptr
	s_cmp_eq_u32 s32, 2
	s_cbranch_scc1 .Lg_ptr
	s_cmp_eq_u32 s32, 4
	s_cbranch_scc1 .Lg_ptr
	s_cmp_lg_u32 s32, 26
	s_cbranch_scc1 .Lg_noptr
.Lg_ptr:
	s_movk_i32 s98, 0x78
	s_cmp_lt_u32 s32, 26
	s_cselect_b32 s98, 0x60, s98
	s_cmp_lt_u32 s32, 4
	s_cselect_b32 s98, 0x50, s98
	s_movk_i32 s99, 0x58
	s_cselect_b32 s99, 0x48, s99
	s_cmp_lt_u32 s32, 2
	s_cselect_b32 s99, 64, s99
	s_load_dwordx2 s[88:89], s[100:101], s98
	s_load_dwordx2 s[94:95], s[100:101], s99
	s_waitcnt lgkmcnt(0)
.Lg_noptr:
	v_readfirstlane_b32 s98, v0
	s_and_b32 s72, s2, 0xff
	s_lshl_b32 s72, s72, 1
	s_lshr_b32 s98, s98, 6
	s_and_b32 s73, s98, 3
	s_lshr_b32 s98, s98, 2
	s_or_b32 s72, s72, s98
	s_cmp_lt_u32 s32, 4
	s_cbranch_scc1 .Lg_t0
	s_cmp_lt_u32 s32, 26
	s_cbranch_scc1 .Lg_t1
	s_add_i32 s98, s32, -26
	s_lshl_b32 s98, s98, 9
	s_add_i32 s98, s98, s72
	s_lshr_b32 s74, s98, 6
	s_and_b32 s75, s98, 63
	s_mov_b32 s90, 0x2000
	s_mov_b32 s84, 0x2c00
	s_mov_b32 s85, 1
	s_lshl_b32 s98, s74, 19
	s_lshl_b32 s99, s75, 7
	s_add_i32 s98, s98, s99
	s_mul_i32 s99, s75, 0x58000
	s_lshl_b32 s82, s74, 7
	s_add_i32 s99, s99, s82
	s_add_i32 s99, s99, 0x6900000
	s_mov_b32 s74, 0
	s_branch .Lg_tdone
.Lg_t1:
	s_add_i32 s98, s32, -4
	s_lshl_b32 s98, s98, 9
	s_add_i32 s98, s98, s72
	s_mul_hi_u32 s74, s98, 0xba2e8c
	s_mul_i32 s99, s74, 0x160
	s_sub_i32 s75, s98, s99
	s_mov_b32 s90, 0xb000
	s_mov_b32 s84, 0x1000
	s_mov_b32 s85, 0
	s_bfe_u32 s98, s75, 0x10002
	s_mul_i32 s98, s98, 0x5800
	s_lshr_b32 s99, s75, 3
	s_lshl_b32 s99, s99, 9
	s_add_i32 s98, s98, s99
	s_and_b32 s99, s75, 3
	s_lshl_b32 s99, s99, 7
	s_add_i32 s98, s98, s99
	s_mul_i32 s99, s74, 0x2c0000
	s_add_i32 s98, s98, s99
	s_lshl_b32 s99, s75, 17
	s_lshl_b32 s82, s74, 7
	s_add_i32 s99, s99, s82
	s_add_i32 s99, s99, 0x3d00000
	s_lshl_b32 s74, s74, 8
	s_branch .Lg_tdone
.Lg_t0:
	s_lshl_b32 s98, s32, 9
	s_add_i32 s98, s98, s72
	s_lshr_b32 s74, s98, 6
	s_and_b32 s75, s98, 63
	s_mov_b32 s90, 0x2000
	s_mov_b32 s84, 0x1000
	s_mov_b32 s85, 0
	s_lshl_b32 s98, s74, 19
	s_lshl_b32 s99, s75, 7
	s_add_i32 s98, s98, s99
	s_lshl_b32 s99, s75, 17
	s_lshl_b32 s82, s74, 7
	s_add_i32 s99, s99, s82
	s_add_i32 s99, s99, 0x3500000
	s_lshl_b32 s82, s74, 8
	s_cmp_lt_u32 s74, 16
	s_cselect_b32 s74, 0, 0x1000
	s_sub_i32 s74, s82, s74
.Lg_tdone:
	s_add_u32 s82, s28, s99
	s_addc_u32 s83, s29, 0
	s_lshl_b32 s99, s73, 4
	s_mul_i32 s99, s99, s90
	s_add_i32 s98, s98, s99
	s_lshl_b32 s99, s73, 6
	s_add_i32 s99, s99, s74
	s_add_u32 s72, s88, s98
	s_addc_u32 s73, s89, 0
	s_add_u32 s74, s72, s90
	s_addc_u32 s75, s73, 0
	s_add_u32 s98, s94, s99
	s_addc_u32 s99, s95, 0
	v_and_b32_e32 v76, 63, v0
	v_lshrrev_b32_e32 v77, 3, v76
	v_and_b32_e32 v78, 7, v76
	s_lshl_b32 s90, s90, 1
	v_lshlrev_b32_e32 v78, 4, v78
	v_mad_u32_u24 v79, v77, s90, v78
	v_lshlrev_b32_e32 v80, 3, v77
	s_nop 0
	global_load_dwordx4 v[238:241], v79, s[72:73] nt
	global_load_dwordx4 v[242:245], v79, s[74:75] nt
	global_load_dwordx2 v[250:251], v80, s[98:99]
; template <int G> __device__ __forceinline__ void fin_gap(f32x16& P0, f32x16& P1, float (&sacc)[4], unsigned (&cv)[16], u32x4 (&pw)[4]) {
;   if constexpr (G < 16) { P1[G] = __builtin_amdgcn_exp2f(P1[G]); sacc[G & 3] += P0[G]; }
;   else { constexpr int r = 2 * (G - 16); sacc[r & 3] += P1[r]; sacc[(r + 1) & 3] += P1[r + 1]; }
;   if constexpr (G < 4) cv[G] = cvtpk_c(P0[2 * G], P0[2 * G + 1]);
;   else if constexpr (G >= 6 && G < 10) { constexpr int i = G - 2; cv[i] = cvtpk_c(P0[2 * i], P0[2 * i + 1]); }
;   else if constexpr (G >= 12 && G < 16) { constexpr int i = G - 4, j = i - 8; cv[i] = cvtpk_c(P1[2 * j], P1[2 * j + 1]); }
;   else if constexpr (G >= 18 && G < 22) { constexpr int i = G - 6, j = i - 8; cv[i] = cvtpk_c(P1[2 * j], P1[2 * j + 1]); }
;   if constexpr (G == 4 || G == 10 || G == 16 || G == 22) { constexpr int q = (G - 4) / 6; auto r0 = __builtin_amdgcn_permlane32_swap(cv[4 * q], cv[4 * q + 2], false, false); pw[q].x = r0[0]; pw[q].z = r0[1]; }
;   if constexpr (G == 5 || G == 11 || G == 17 || G == 23) { constexpr int q = (G - 5) / 6; auto r1 = __builtin_amdgcn_permlane32_swap(cv[4 * q + 1], cv[4 * q + 3], false, false); pw[q].y = r1[0]; pw[q].w = r1[1]; }
; }
.Lg_inc:
	s_add_i32 s87, s87, 1
	s_add_i32 s32, s32, 1
	v_exp_f32_e32 v1, v249
	v_exp_f32_e32 v101, v84
	v_exp_f32_e32 v103, v85
	v_exp_f32_e32 v205, v89
	v_exp_f32_e32 v206, v90
	v_sub_f32_e32 v102, v70, v140
	v_sub_f32_e32 v204, v74, v140
	v_exp_f32_e32 v160, v88
	v_sub_f32_e32 v88, v69, v140
	v_sub_f32_e32 v158, v72, v140
	v_exp_f32_e32 v154, v86
	v_exp_f32_e32 v159, v87
	v_exp_f32_e32 v208, v91
	v_exp_f32_e32 v209, v92
	v_exp_f32_e32 v210, v93
	v_exp_f32_e32 v211, v94
	v_sub_f32_e32 v155, v71, v140
	v_sub_f32_e32 v161, v73, v140
	v_sub_f32_e32 v207, v75, v140
	ds_read_b128 v[68:71], v178 offset:32768
	ds_read_b128 v[84:87], v178 offset:36864
	s_waitcnt lgkmcnt(0)
	ds_read_b128 v[104:107], v179 offset:32768
	ds_read_b128 v[108:111], v179 offset:36864
	v_mfma_f32_32x32x16_bf16 v[68:83], v[68:71], v[126:129], 0
	v_cvt_pk_bf16_f32 v100, v1, v101
	v_exp_f32_e32 v226, v99
	v_add_f32_e32 v227, 0, v1
	v_exp_f32_e32 v1, v88
	v_mfma_f32_32x32x16_bf16 v[84:99], v[84:87], v[126:129], 0
	v_add_f32_e32 v228, 0, v101
	v_cvt_pk_bf16_f32 v101, v103, v154
	s_waitcnt lgkmcnt(0)
	ds_read_b128 v[130:133], v177 offset:32768
	ds_read_b128 v[150:153], v177 offset:36864
	v_mfma_f32_32x32x16_bf16 v[68:83], v[104:107], v[122:125], v[68:83]
	v_exp_f32_e32 v229, v102
	v_cvt_pk_bf16_f32 v102, v159, v160
	v_add_f32_e32 v230, 0, v103
	v_mfma_f32_32x32x16_bf16 v[84:99], v[108:111], v[122:125], v[84:99]
	v_add_f32_e32 v105, 0, v154
	v_cvt_pk_bf16_f32 v103, v205, v206
	v_exp_f32_e32 v231, v155
	s_waitcnt lgkmcnt(0)
	ds_read_b128 v[106:109], v176 offset:32768
	ds_read_b128 v[154:157], v176 offset:36864
	v_mfma_f32_32x32x16_bf16 v[68:83], v[130:133], v[118:121], v[68:83]
	v_permlane32_swap_b32_e32 v100, v102
	v_exp_f32_e32 v232, v158
	v_add_f32_e32 v227, v159, v227
	v_mfma_f32_32x32x16_bf16 v[84:99], v[150:153], v[118:121], v[84:99]
	v_permlane32_swap_b32_e32 v101, v103
	v_exp_f32_e32 v233, v161
	v_add_f32_e32 v228, v160, v228
	s_waitcnt lgkmcnt(0)
	ds_read_b128 v[130:133], v178 offset:40960
	ds_read_b128 v[150:153], v178 offset:45056
	ds_read_b128 v[158:161], v171
	v_mfma_f32_32x32x16_bf16 v[68:83], v[106:109], v[114:117], v[68:83]
	v_cvt_pk_bf16_f32 v104, v208, v209
	v_exp_f32_e32 v234, v204
	v_add_f32_e32 v230, v205, v230
	v_mfma_f32_32x32x16_bf16 v[84:99], v[154:157], v[114:117], v[84:99]
	v_add_f32_e32 v236, v206, v105
	v_cvt_pk_bf16_f32 v105, v210, v211
	v_exp_f32_e32 v235, v207
	s_waitcnt lgkmcnt(0)
	ds_read_b128 v[108:111], v179 offset:40960
	ds_read_b128 v[154:157], v179 offset:45056
	ds_read_b128 v[204:207], v170
	v_mfma_f32_32x32x16_bf16 v[68:83], v[130:133], v[158:161], v[68:83]
	v_cvt_pk_bf16_f32 v106, v212, v213
	v_exp_f32_e32 v216, v216
	v_add_f32_e32 v227, v208, v227
	v_mfma_f32_32x32x16_bf16 v[84:99], v[150:153], v[158:161], v[84:99]
	v_cvt_pk_bf16_f32 v107, v214, v215
	v_exp_f32_e32 v217, v217
	v_add_f32_e32 v228, v209, v228
	s_waitcnt lgkmcnt(0)
	ds_read_b128 v[130:133], v177 offset:40960
	ds_read_b128 v[150:153], v177 offset:45056
	ds_read_b128 v[158:161], v169
	v_mfma_f32_32x32x16_bf16 v[68:83], v[108:111], v[204:207], v[68:83]
	v_permlane32_swap_b32_e32 v104, v106
	v_exp_f32_e32 v218, v218
	v_add_f32_e32 v230, v210, v230
	v_mfma_f32_32x32x16_bf16 v[84:99], v[154:157], v[204:207], v[84:99]
	v_add_f32_e32 v111, v211, v236
	v_permlane32_swap_b32_e32 v105, v107
	v_exp_f32_e32 v219, v219
	s_waitcnt lgkmcnt(0)
	ds_read_b128 v[154:157], v176 offset:40960
	ds_read_b128 v[204:207], v176 offset:45056
	ds_read_b128 v[208:211], v168
	v_mfma_f32_32x32x16_bf16 v[68:83], v[130:133], v[158:161], v[68:83]
	v_cvt_pk_bf16_f32 v108, v226, v1
	v_exp_f32_e32 v220, v220
	v_add_f32_e32 v212, v212, v227
	v_mfma_f32_32x32x16_bf16 v[84:99], v[150:153], v[158:161], v[84:99]
	v_cvt_pk_bf16_f32 v109, v229, v231
	v_exp_f32_e32 v221, v221
	v_add_f32_e32 v213, v213, v228
	s_waitcnt lgkmcnt(0)
	ds_read_b128 v[130:133], v178 offset:49152
	ds_read_b128 v[150:153], v178 offset:53248
	ds_read_b128 v[158:161], v171 offset:4096
	v_mfma_f32_32x32x16_bf16 v[68:83], v[154:157], v[208:211], v[68:83]
	v_cvt_pk_bf16_f32 v110, v232, v233
	v_exp_f32_e32 v222, v222
	v_add_f32_e32 v214, v214, v230
	v_mfma_f32_32x32x16_bf16 v[84:99], v[204:207], v[208:211], v[84:99]
	v_add_f32_e32 v215, v215, v111
	v_cvt_pk_bf16_f32 v111, v234, v235
	v_exp_f32_e32 v223, v223
	s_waitcnt lgkmcnt(0)
	ds_read_b128 v[154:157], v179 offset:49152
	ds_read_b128 v[204:207], v179 offset:53248
	ds_read_b128 v[208:211], v170 offset:4096
	v_mfma_f32_32x32x16_bf16 v[68:83], v[130:133], v[158:161], v[68:83]
	v_add_f32_e32 v1, v1, v213
	v_permlane32_swap_b32_e32 v108, v110
	v_add_f32_e32 v226, v226, v212
	v_mfma_f32_32x32x16_bf16 v[84:99], v[150:153], v[158:161], v[84:99]
	v_add_f32_e32 v131, v229, v214
	v_add_f32_e32 v132, v231, v215
	v_permlane32_swap_b32_e32 v109, v111
	s_waitcnt lgkmcnt(0)
	ds_read_b128 v[150:153], v177 offset:49152
	ds_read_b128 v[158:161], v177 offset:53248
	ds_read_b128 v[212:215], v169 offset:4096
	v_mfma_f32_32x32x16_bf16 v[68:83], v[154:157], v[208:211], v[68:83]
	v_add_f32_e32 v133, v232, v226
	v_add_f32_e32 v1, v233, v1
	v_cvt_pk_bf16_f32 v130, v216, v217
	v_mfma_f32_32x32x16_bf16 v[84:99], v[204:207], v[208:211], v[84:99]
	v_add_f32_e32 v226, v234, v131
	v_cvt_pk_bf16_f32 v131, v218, v219
	v_add_f32_e32 v227, v235, v132
	s_waitcnt lgkmcnt(0)
	ds_read_b128 v[154:157], v176 offset:49152
	ds_read_b128 v[204:207], v176 offset:53248
	ds_read_b128 v[208:211], v168 offset:4096
	v_mfma_f32_32x32x16_bf16 v[68:83], v[150:153], v[212:215], v[68:83]
	v_add_f32_e32 v1, v217, v1
	v_cvt_pk_bf16_f32 v132, v220, v221
	v_add_f32_e32 v216, v216, v133
	v_mfma_f32_32x32x16_bf16 v[84:99], v[158:161], v[212:215], v[84:99]
	v_cvt_pk_bf16_f32 v133, v222, v223
	v_add_f32_e32 v150, v218, v226
	v_add_f32_e32 v151, v219, v227
	s_waitcnt lgkmcnt(0)
	v_mfma_f32_32x32x16_bf16 v[68:83], v[154:157], v[208:211], v[68:83]
	v_add_f32_e32 v1, v221, v1
	v_permlane32_swap_b32_e32 v130, v132
	v_add_f32_e32 v152, v220, v216
	v_mfma_f32_32x32x16_bf16 v[84:99], v[204:207], v[208:211], v[84:99]
	v_permlane32_swap_b32_e32 v131, v133
	v_add_f32_e32 v150, v222, v150
	v_add_f32_e32 v151, v223, v151
	v_add_f32_e32 v1, v152, v1
	v_add_f32_e32 v150, v150, v151
	v_add_f32_e32 v205, v1, v150
	v_mov_b32_e32 v206, v205
	s_nop 1
	v_permlane32_swap_b32_e32 v205, v206

.LBB0_764:
	s_lshr_b32 s98, s2, 8
	s_mul_i32 s98, s98, 18
	s_add_i32 s98, s98, 19
	s_cmp_le_u32 s32, s98
	s_cbranch_scc1 .Lg_w3
	s_waitcnt vmcnt(0)
	s_branch .Lg_wd

; #define GAS __attribute__((address_space(1)))
; __device__ __forceinline__ unsigned cvt_pk_bf16(float lo, float hi) { unsigned r; asm volatile("v_cvt_pk_bf16_f32 %0, %1, %2" : "=v"(r) : "v"(lo), "v"(hi)); return r; }
; template <int NB>
; __device__ __forceinline__ void p0_batch(int it0, int stride, int lane, const P0Ptrs& a) {
;     ...
;         if (d[q].dst) {
; #pragma unroll
;             for (int e = 0; e < 4; ++e) { u32x4 o; o.x = cvt_pk_bf16(v[q][0][e], v[q][1][e]); o.y = cvt_pk_bf16(v[q][2][e], v[q][3][e]); o.z = cvt_pk_bf16(v[q][4][e], v[q][5][e]); o.w = cvt_pk_bf16(v[q][6][e], v[q][7][e]);
;                 *(GAS u32x4*)(d[q].dst + (size_t)e * d[q].ldt) = o; } }
;     }
.LBB0_766:
	s_cmp_lt_u32 s87, 2
	s_cbranch_scc1 .Lg_bdone
	s_lshr_b32 s98, s2, 8
	s_mul_i32 s98, s98, 18
	s_add_i32 s98, s98, 20
	s_cmp_gt_u32 s32, s98
	s_cbranch_scc1 .Lg_bdone
	v_readfirstlane_b32 s98, v0
	v_and_b32_e32 v84, 63, v0
	v_lshrrev_b32_e32 v85, 3, v84
	v_and_b32_e32 v86, 7, v84
	v_lshlrev_b32_e32 v86, 4, v86
	s_lshr_b32 s98, s98, 6
	s_and_b32 s99, s98, 3
	s_cmp_lt_u32 s98, 4
	s_mov_b32 s98, 0x26400
	s_cselect_b32 s98, 0x1e800, s98
	s_lshl_b32 s99, s99, 3
	s_mul_i32 s72, s99, 0x90
	s_add_i32 s98, s98, s72
	v_mul_u32_u24_e32 v87, 0x90, v85
	v_add3_u32 v87, v87, v86, s98
	v_mad_u32_u24 v88, v85, s91, v86
	ds_read_b128 v[100:103], v87
	s_mul_i32 s99, s99, s91
	s_add_u32 s98, s92, s99
	s_addc_u32 s99, s93, 0
	s_waitcnt lgkmcnt(0)
	global_store_dwordx4 v88, v[100:103], s[98:99]
